# E60: prompt-FoX loop: next-tile K/V address arithmetic and global loads moved from the loop top to just after the bias/K-fragment LDS reads are issued (VALU under LDS latency); on E41
# speedup vs baseline: 1.0332x; 1.0332x over previous
.LBB0_1390:
	s_cmp_le_i32 s16, s15
	s_cselect_b64 s[20:21], -1, 0
	s_and_b64 s[20:21], s[84:85], s[20:21]
	s_andn2_b64 vcc, exec, s[20:21]
	s_cbranch_vccnz .Lfxg_skip
	s_bitcmp1_b32 s18, 0
	s_cselect_b32 s18, 0xa800, 0
	s_add_i32 s70, s18, 0
	ds_read_b128 v[82:85], v198
	ds_read_b128 v[86:89], v198 offset:32
	ds_read_b128 v[90:93], v198 offset:64
	ds_read_b128 v[94:97], v198 offset:96
	v_add3_u32 v2, s70, v214, v186
	ds_read_b128 v[226:229], v2
	ds_read_b128 v[230:233], v2 offset:32
	ds_read_b128 v[234:237], v2 offset:64
	ds_read_b128 v[238:241], v2 offset:96
	ds_read_b128 v[50:53], v198 offset:128
	ds_read_b128 v[54:57], v198 offset:160
	ds_read_b128 v[58:61], v198 offset:192
	ds_read_b128 v[62:65], v198 offset:224
	s_cmp_eq_u64 s[90:91], 0
	s_cbranch_scc1 .Lfxg_na
	v_add_u32_e32 v250, s16, v197
	v_ashrrev_i32_e32 v251, 31, v250
	v_lshlrev_b64 v[250:251], 9, v[250:251]
	v_lshl_add_u64 v[250:251], v[250:251], 0, v[148:149]
	v_lshlrev_b64 v[250:251], 1, v[250:251]
	v_lshl_add_u64 v[252:253], s[64:65], 0, v[250:251]
	v_lshl_add_u64 v[250:251], s[66:67], 0, v[250:251]
	global_load_dwordx4 v[134:137], v[250:251], off
	v_add_u32_e32 v250, s16, v196
	v_ashrrev_i32_e32 v251, 31, v250
	v_lshlrev_b64 v[250:251], 9, v[250:251]
	v_lshl_add_u64 v[250:251], v[250:251], 0, v[156:157]
	v_lshlrev_b64 v[250:251], 1, v[250:251]
	global_load_dwordx4 v[130:133], v[252:253], off
	v_lshl_add_u64 v[252:253], s[64:65], 0, v[250:251]
	v_lshl_add_u64 v[250:251], s[66:67], 0, v[250:251]
	global_load_dwordx4 v[138:141], v[252:253], off
	global_load_dwordx4 v[142:145], v[250:251], off
.Lfxg_na:
	s_add_i32 s18, s16, 0x7f
	s_cmp_le_i32 s18, s13
	s_waitcnt lgkmcnt(7)
	v_mfma_f32_32x32x16_bf16 v[82:97], v[226:229], v[114:117], v[82:97]
	ds_read_b128 v[4:7], v2 offset:4608
	s_waitcnt lgkmcnt(7)
	v_mfma_f32_32x32x16_bf16 v[82:97], v[230:233], v[118:121], v[82:97]
	ds_read_b128 v[8:11], v2 offset:4640
	s_waitcnt lgkmcnt(7)
	v_mfma_f32_32x32x16_bf16 v[82:97], v[234:237], v[122:125], v[82:97]
	ds_read_b128 v[12:15], v2 offset:4672
	s_waitcnt lgkmcnt(7)
	v_mfma_f32_32x32x16_bf16 v[82:97], v[238:241], v[126:129], v[82:97]
	ds_read_b128 v[160:163], v2 offset:4704
	ds_read_b128 v[66:69], v198 offset:256
	ds_read_b128 v[70:73], v198 offset:288
	ds_read_b128 v[74:77], v198 offset:320
	ds_read_b128 v[78:81], v198 offset:352
	s_waitcnt lgkmcnt(7)
	v_mfma_f32_32x32x16_bf16 v[50:65], v[4:7], v[114:117], v[50:65]
	ds_read_b128 v[226:229], v2 offset:9216
	s_waitcnt lgkmcnt(7)
	v_mfma_f32_32x32x16_bf16 v[50:65], v[8:11], v[118:121], v[50:65]
	ds_read_b128 v[230:233], v2 offset:9248
	s_waitcnt lgkmcnt(7)
	v_mfma_f32_32x32x16_bf16 v[50:65], v[12:15], v[122:125], v[50:65]
	ds_read_b128 v[234:237], v2 offset:9280
	s_waitcnt lgkmcnt(7)
	v_mfma_f32_32x32x16_bf16 v[50:65], v[160:163], v[126:129], v[50:65]
	ds_read_b128 v[238:241], v2 offset:9312
	ds_read_b128 v[98:101], v198 offset:384
	ds_read_b128 v[102:105], v198 offset:416
	ds_read_b128 v[106:109], v198 offset:448
	ds_read_b128 v[110:113], v198 offset:480
	s_waitcnt lgkmcnt(7)
	v_mfma_f32_32x32x16_bf16 v[66:81], v[226:229], v[114:117], v[66:81]
	ds_read_b128 v[4:7], v2 offset:13824
	s_waitcnt lgkmcnt(7)
	v_mfma_f32_32x32x16_bf16 v[66:81], v[230:233], v[118:121], v[66:81]
	ds_read_b128 v[8:11], v2 offset:13856
	s_waitcnt lgkmcnt(7)
	v_mfma_f32_32x32x16_bf16 v[66:81], v[234:237], v[122:125], v[66:81]
	ds_read_b128 v[12:15], v2 offset:13888
	s_waitcnt lgkmcnt(7)
	v_mfma_f32_32x32x16_bf16 v[66:81], v[238:241], v[126:129], v[66:81]
	ds_read_b128 v[160:163], v2 offset:13920
	s_waitcnt lgkmcnt(3)
	v_mfma_f32_32x32x16_bf16 v[98:113], v[4:7], v[114:117], v[98:113]
	s_waitcnt lgkmcnt(2)
	v_mfma_f32_32x32x16_bf16 v[98:113], v[8:11], v[118:121], v[98:113]
	s_waitcnt lgkmcnt(1)
	v_mfma_f32_32x32x16_bf16 v[98:113], v[12:15], v[122:125], v[98:113]
	s_waitcnt lgkmcnt(0)
	v_mfma_f32_32x32x16_bf16 v[98:113], v[160:163], v[126:129], v[98:113]
	s_cbranch_scc1 .LBB0_1393
	v_cmp_gt_i32_e64 s[46:47], 26, v195
	v_cmp_gt_i32_e64 s[48:49], 27, v195
	v_cmp_gt_i32_e64 s[44:45], 25, v195
	s_and_b64 s[46:47], s[48:49], s[46:47]
	v_cmp_gt_i32_e64 s[42:43], 24, v195
	v_cndmask_b32_e64 v97, v97, v190, s[48:49]
	v_cndmask_b32_e64 v96, v96, v190, s[46:47]
	s_and_b64 s[44:45], s[46:47], s[44:45]
	v_cmp_gt_i32_e64 s[46:47], 58, v195
	v_cmp_gt_i32_e64 s[48:49], 59, v195
	v_cmp_gt_i32_e64 s[40:41], 19, v195
	v_cndmask_b32_e64 v95, v95, v190, s[44:45]
	s_and_b64 s[42:43], s[44:45], s[42:43]
	v_cmp_gt_i32_e64 s[44:45], 57, v195
	s_and_b64 s[46:47], s[48:49], s[46:47]
	v_cmp_gt_i32_e64 s[38:39], 18, v195
	v_cndmask_b32_e64 v94, v94, v190, s[42:43]
	s_and_b64 s[40:41], s[42:43], s[40:41]
	v_cmp_gt_i32_e64 s[42:43], 56, v195
	v_cndmask_b32_e64 v65, v65, v190, s[48:49]
	v_cndmask_b32_e64 v64, v64, v190, s[46:47]
	s_and_b64 s[44:45], s[46:47], s[44:45]
	s_movk_i32 s46, 0x5a
	s_movk_i32 s48, 0x5b
	v_cmp_gt_i32_e64 s[36:37], 17, v195
	v_cndmask_b32_e64 v93, v93, v190, s[40:41]
	s_and_b64 s[38:39], s[40:41], s[38:39]
	v_cmp_gt_i32_e64 s[40:41], 51, v195
	v_cndmask_b32_e64 v63, v63, v190, s[44:45]
	s_and_b64 s[42:43], s[44:45], s[42:43]
	s_movk_i32 s44, 0x59
	v_cmp_gt_i32_e64 s[46:47], s46, v195
	v_cmp_gt_i32_e64 s[48:49], s48, v195
	v_cmp_gt_i32_e64 s[34:35], 16, v195
	v_cndmask_b32_e64 v92, v92, v190, s[38:39]
	s_and_b64 s[36:37], s[38:39], s[36:37]
	v_cmp_gt_i32_e64 s[38:39], 50, v195
	v_cndmask_b32_e64 v62, v62, v190, s[42:43]
	s_and_b64 s[40:41], s[42:43], s[40:41]
	s_movk_i32 s42, 0x58
	v_cmp_gt_i32_e64 s[44:45], s44, v195
	s_and_b64 s[46:47], s[48:49], s[46:47]
	v_cmp_gt_i32_e64 s[30:31], 11, v195
	v_cndmask_b32_e64 v91, v91, v190, s[36:37]
	s_and_b64 s[34:35], s[36:37], s[34:35]
	v_cmp_gt_i32_e64 s[36:37], 49, v195
	v_cndmask_b32_e64 v61, v61, v190, s[40:41]
	s_and_b64 s[38:39], s[40:41], s[38:39]
	s_movk_i32 s40, 0x53
	v_cmp_gt_i32_e64 s[42:43], s42, v195
	s_and_b64 s[44:45], s[46:47], s[44:45]
	v_cmp_gt_i32_e64 s[28:29], 10, v195
	v_cndmask_b32_e64 v90, v90, v190, s[34:35]
	s_and_b64 s[30:31], s[34:35], s[30:31]
	v_cmp_gt_i32_e64 s[34:35], 48, v195
	v_cndmask_b32_e64 v60, v60, v190, s[38:39]
	s_and_b64 s[36:37], s[38:39], s[36:37]
	s_movk_i32 s38, 0x52
	v_cmp_gt_i32_e64 s[40:41], s40, v195
	v_cndmask_b32_e64 v81, v81, v190, s[48:49]
	v_cndmask_b32_e64 v80, v80, v190, s[46:47]
	s_and_b64 s[42:43], s[44:45], s[42:43]
	s_movk_i32 s46, 0x7a
	s_movk_i32 s48, 0x7b
	v_cmp_gt_i32_e64 s[26:27], 9, v195
	v_cndmask_b32_e64 v89, v89, v190, s[30:31]
	s_and_b64 s[28:29], s[30:31], s[28:29]
	v_cmp_gt_i32_e64 s[30:31], 43, v195
	v_cndmask_b32_e64 v59, v59, v190, s[36:37]
	s_and_b64 s[34:35], s[36:37], s[34:35]
	s_movk_i32 s36, 0x51
	v_cmp_gt_i32_e64 s[38:39], s38, v195
	v_cndmask_b32_e64 v79, v79, v190, s[44:45]
	s_and_b64 s[40:41], s[42:43], s[40:41]
	s_movk_i32 s44, 0x79
	v_cmp_gt_i32_e64 s[46:47], s46, v195
	v_cmp_gt_i32_e64 s[48:49], s48, v195
	v_cmp_gt_i32_e64 s[24:25], 8, v195
	v_cndmask_b32_e64 v88, v88, v190, s[28:29]
	s_and_b64 s[26:27], s[28:29], s[26:27]
	v_cmp_gt_i32_e64 s[28:29], 42, v195
	v_cndmask_b32_e64 v58, v58, v190, s[34:35]
	s_and_b64 s[30:31], s[34:35], s[30:31]
	s_movk_i32 s34, 0x50
	v_cmp_gt_i32_e64 s[36:37], s36, v195
	v_cndmask_b32_e64 v78, v78, v190, s[42:43]
	s_and_b64 s[38:39], s[40:41], s[38:39]
	s_movk_i32 s42, 0x78
	v_cmp_gt_i32_e64 s[44:45], s44, v195
	s_and_b64 s[46:47], s[48:49], s[46:47]
	v_cmp_gt_i32_e64 s[22:23], 3, v195
	v_cndmask_b32_e64 v87, v87, v190, s[26:27]
	s_and_b64 s[24:25], s[26:27], s[24:25]
	v_cmp_gt_i32_e64 s[26:27], 41, v195
	v_cndmask_b32_e64 v57, v57, v190, s[30:31]
	s_and_b64 s[28:29], s[30:31], s[28:29]
	s_movk_i32 s30, 0x4b
	v_cmp_gt_i32_e64 s[34:35], s34, v195
	v_cndmask_b32_e64 v77, v77, v190, s[40:41]
	s_and_b64 s[36:37], s[38:39], s[36:37]
	s_movk_i32 s40, 0x73
	v_cmp_gt_i32_e64 s[42:43], s42, v195
	s_and_b64 s[44:45], s[46:47], s[44:45]
	v_cmp_gt_i32_e64 s[20:21], 2, v195
	v_cndmask_b32_e64 v86, v86, v190, s[24:25]
	s_and_b64 s[22:23], s[24:25], s[22:23]
	v_cmp_gt_i32_e64 s[24:25], 40, v195
	v_cndmask_b32_e64 v56, v56, v190, s[28:29]
	s_and_b64 s[26:27], s[28:29], s[26:27]
	s_movk_i32 s28, 0x4a
	v_cmp_gt_i32_e64 s[30:31], s30, v195
	v_cndmask_b32_e64 v76, v76, v190, s[38:39]
	s_and_b64 s[34:35], s[36:37], s[34:35]
	s_movk_i32 s38, 0x72
	v_cmp_gt_i32_e64 s[40:41], s40, v195
	s_and_b64 s[42:43], s[44:45], s[42:43]
	v_cmp_gt_i32_e64 s[18:19], 1, v195
	v_cndmask_b32_e64 v85, v85, v190, s[22:23]
	s_and_b64 s[20:21], s[22:23], s[20:21]
	v_cmp_gt_i32_e64 s[22:23], 35, v195
	v_cndmask_b32_e64 v55, v55, v190, s[26:27]
	s_and_b64 s[24:25], s[26:27], s[24:25]
	s_movk_i32 s26, 0x49
	v_cmp_gt_i32_e64 s[28:29], s28, v195
	v_cndmask_b32_e64 v75, v75, v190, s[36:37]
	s_and_b64 s[30:31], s[34:35], s[30:31]
	s_movk_i32 s36, 0x71
	v_cmp_gt_i32_e64 s[38:39], s38, v195
	s_and_b64 s[40:41], s[42:43], s[40:41]
	v_cmp_gt_i32_e32 vcc, 0, v195
	v_cndmask_b32_e64 v84, v84, v190, s[20:21]
	s_and_b64 s[18:19], s[20:21], s[18:19]
	v_cmp_gt_i32_e64 s[20:21], 34, v195
	v_cndmask_b32_e64 v54, v54, v190, s[24:25]
	s_and_b64 s[22:23], s[24:25], s[22:23]
	s_movk_i32 s24, 0x48
	v_cmp_gt_i32_e64 s[26:27], s26, v195
	v_cndmask_b32_e64 v74, v74, v190, s[34:35]
	s_and_b64 s[28:29], s[30:31], s[28:29]
	s_movk_i32 s34, 0x70
	v_cmp_gt_i32_e64 s[36:37], s36, v195
	s_and_b64 s[38:39], s[40:41], s[38:39]
	v_cndmask_b32_e64 v83, v83, v190, s[18:19]
	s_and_b64 vcc, s[18:19], vcc
	v_cmp_gt_i32_e64 s[18:19], 33, v195
	v_cndmask_b32_e64 v53, v53, v190, s[22:23]
	s_and_b64 s[20:21], s[22:23], s[20:21]
	s_movk_i32 s22, 0x43
	v_cmp_gt_i32_e64 s[24:25], s24, v195
	v_cndmask_b32_e64 v73, v73, v190, s[30:31]
	s_and_b64 s[26:27], s[28:29], s[26:27]
	s_movk_i32 s30, 0x6b
	v_cmp_gt_i32_e64 s[34:35], s34, v195
	s_and_b64 s[36:37], s[38:39], s[36:37]
	v_cndmask_b32_e32 v82, v82, v190, vcc
	v_cmp_gt_i32_e32 vcc, 32, v195
	v_cndmask_b32_e64 v52, v52, v190, s[20:21]
	s_and_b64 s[18:19], s[20:21], s[18:19]
	s_movk_i32 s20, 0x42
	v_cmp_gt_i32_e64 s[22:23], s22, v195
	v_cndmask_b32_e64 v72, v72, v190, s[28:29]
	s_and_b64 s[24:25], s[26:27], s[24:25]
	s_movk_i32 s28, 0x6a
	v_cmp_gt_i32_e64 s[30:31], s30, v195
	s_and_b64 s[34:35], s[36:37], s[34:35]
	v_cndmask_b32_e64 v51, v51, v190, s[18:19]
	s_and_b64 vcc, s[18:19], vcc
	s_movk_i32 s18, 0x41
	v_cmp_gt_i32_e64 s[20:21], s20, v195
	v_cndmask_b32_e64 v71, v71, v190, s[26:27]
	s_and_b64 s[22:23], s[24:25], s[22:23]
	s_movk_i32 s26, 0x69
	v_cmp_gt_i32_e64 s[28:29], s28, v195
	s_and_b64 s[30:31], s[34:35], s[30:31]
	v_cmp_gt_i32_e64 s[18:19], s18, v195
	v_cndmask_b32_e64 v70, v70, v190, s[24:25]
	s_and_b64 s[20:21], s[22:23], s[20:21]
	s_movk_i32 s24, 0x68
	v_cmp_gt_i32_e64 s[26:27], s26, v195
	s_and_b64 s[28:29], s[30:31], s[28:29]
	v_cndmask_b32_e32 v50, v50, v190, vcc
	v_cmp_gt_i32_e32 vcc, 64, v195
	v_cndmask_b32_e64 v69, v69, v190, s[22:23]
	s_and_b64 s[18:19], s[20:21], s[18:19]
	s_movk_i32 s22, 0x63
	v_cmp_gt_i32_e64 s[24:25], s24, v195
	s_and_b64 s[26:27], s[28:29], s[26:27]
	v_cndmask_b32_e64 v68, v68, v190, s[20:21]
	v_cndmask_b32_e64 v67, v67, v190, s[18:19]
	s_and_b64 vcc, s[18:19], vcc
	s_movk_i32 s18, 0x60
	s_movk_i32 s20, 0x62
	v_cmp_gt_i32_e64 s[22:23], s22, v195
	s_and_b64 s[24:25], s[26:27], s[24:25]
	v_cndmask_b32_e32 v66, v66, v190, vcc
	v_cmp_gt_i32_e32 vcc, s18, v195
	s_movk_i32 s18, 0x61
	v_cmp_gt_i32_e64 s[20:21], s20, v195
	s_and_b64 s[22:23], s[24:25], s[22:23]
	v_cmp_gt_i32_e64 s[18:19], s18, v195
	s_and_b64 s[20:21], s[22:23], s[20:21]
	s_and_b64 s[18:19], s[20:21], s[18:19]
	s_and_b64 vcc, s[18:19], vcc
	v_cndmask_b32_e64 v113, v113, v190, s[48:49]
	v_cndmask_b32_e64 v112, v112, v190, s[46:47]
	v_cndmask_b32_e64 v111, v111, v190, s[44:45]
	v_cndmask_b32_e64 v110, v110, v190, s[42:43]
	v_cndmask_b32_e64 v109, v109, v190, s[40:41]
	v_cndmask_b32_e64 v108, v108, v190, s[38:39]
	v_cndmask_b32_e64 v107, v107, v190, s[36:37]
	v_cndmask_b32_e64 v106, v106, v190, s[34:35]
	v_cndmask_b32_e64 v105, v105, v190, s[30:31]
	v_cndmask_b32_e64 v104, v104, v190, s[28:29]
	v_cndmask_b32_e64 v103, v103, v190, s[26:27]
	v_cndmask_b32_e64 v102, v102, v190, s[24:25]
	v_cndmask_b32_e64 v101, v101, v190, s[22:23]
	v_cndmask_b32_e64 v100, v100, v190, s[20:21]
	v_cndmask_b32_e64 v99, v99, v190, s[18:19]
	v_cndmask_b32_e32 v98, v98, v190, vcc

.Lfxg_skip:
	s_cmp_eq_u64 s[90:91], 0
	s_cbranch_scc1 .Lfxg_nb
	v_add_u32_e32 v250, s16, v197
	v_ashrrev_i32_e32 v251, 31, v250
	v_lshlrev_b64 v[250:251], 9, v[250:251]
	v_lshl_add_u64 v[250:251], v[250:251], 0, v[148:149]
	v_lshlrev_b64 v[250:251], 1, v[250:251]
	v_lshl_add_u64 v[252:253], s[64:65], 0, v[250:251]
	v_lshl_add_u64 v[250:251], s[66:67], 0, v[250:251]
	global_load_dwordx4 v[134:137], v[250:251], off
	v_add_u32_e32 v250, s16, v196
	v_ashrrev_i32_e32 v251, 31, v250
	v_lshlrev_b64 v[250:251], 9, v[250:251]
	v_lshl_add_u64 v[250:251], v[250:251], 0, v[156:157]
	v_lshlrev_b64 v[250:251], 1, v[250:251]
	global_load_dwordx4 v[130:133], v[252:253], off
	v_lshl_add_u64 v[252:253], s[64:65], 0, v[250:251]
	v_lshl_add_u64 v[250:251], s[66:67], 0, v[250:251]
	global_load_dwordx4 v[138:141], v[252:253], off
	global_load_dwordx4 v[142:145], v[250:251], off
